# MLA loop: PV MFMAs start after the first 16 keys' exps (probabilities packed per 16-key quarter), remaining exps of the first half under those MFMAs
# baseline (speedup 1.0000x reference)
; #define MFMA(a, b, c) __builtin_amdgcn_mfma_f32_32x32x16_bf16((a), (b), (c), 0, 0, 0)
; DI unsigned pk2(float a, float b) { f2_t v = {a, b}; bf2_t r = __builtin_convertvector(v, bf2_t); return __builtin_bit_cast(unsigned, r); }
; DI float xhalf_sum(float x) { const auto rr = __builtin_amdgcn_permlane32_swap(__float_as_uint(x), __float_as_uint(x), false, false); return __uint_as_float(rr[0]) + __uint_as_float(rr[1]); }
; template <int DQK, int DV, bool BAND> ...
;     ...
;       const float m_ref = (m_run == -INFINITY) ? 0.f : m_run;
;       float rs0 = 0.f, rs1 = 0.f;
; #pragma unroll
;       for (int r = 0; r < 16; ++r) { const float e0 = __builtin_amdgcn_exp2f(p0[r] - m_ref), e1 = __builtin_amdgcn_exp2f(p1[r] - m_ref); p0[r] = e0; p1[r] = e1; rs0 += e0; rs1 += e1; }
;       l_run += xhalf_sum(rs0 + rs1);
;       __builtin_amdgcn_s_setprio(1);
; #pragma unroll
;       for (int s = 0; s < 2; ++s) {
;         const u32x4 pu0 = {pk2(p0[8 * s], p0[8 * s + 1]), pk2(p0[8 * s + 2], p0[8 * s + 3]), pk2(p0[8 * s + 4], p0[8 * s + 5]), pk2(p0[8 * s + 6], p0[8 * s + 7])};
;         const u32x4 pu1 = {pk2(p1[8 * s], p1[8 * s + 1]), pk2(p1[8 * s + 2], p1[8 * s + 3]), pk2(p1[8 * s + 4], p1[8 * s + 5]), pk2(p1[8 * s + 6], p1[8 * s + 7])};
; #pragma unroll
;         for (int cb = 0; cb < NCB; ++cb) {
;           const u32x2 lo0 = *(const u32x2*)&Vs[(cb * 32 + r32) * VLD + 16 * s + 4 * hi];
;           const u32x2 hi0 = *(const u32x2*)&Vs[(cb * 32 + r32) * VLD + 16 * s + 4 * hi + 8];
;           const u32x4 v0 = {lo0[0], lo0[1], hi0[0], hi0[1]};
;           o[cb] = MFMA(__builtin_bit_cast(bf16x8, pu0), __builtin_bit_cast(bf16x8, v0), o[cb]);
;         }
; #pragma unroll
;         for (int cb = 0; cb < NCB; ++cb) {
;           const u32x2 lo1 = *(const u32x2*)&Vs[(cb * 32 + r32) * VLD + 32 + 16 * s + 4 * hi];
;           const u32x2 hi1 = *(const u32x2*)&Vs[(cb * 32 + r32) * VLD + 32 + 16 * s + 4 * hi + 8];
;           const u32x4 v1 = {lo1[0], lo1[1], hi1[0], hi1[1]};
;           o[cb] = MFMA(__builtin_bit_cast(bf16x8, pu1), __builtin_bit_cast(bf16x8, v1), o[cb]);
;         }
;       }
;       __builtin_amdgcn_s_setprio(0);
.LBB1_325:
	v_exp_f32_e32 v34, v34
	v_exp_f32_e32 v35, v35
	v_exp_f32_e32 v36, v36
	v_exp_f32_e32 v37, v37
	v_exp_f32_e32 v38, v38
	v_exp_f32_e32 v39, v39
	v_exp_f32_e32 v40, v40
	v_exp_f32_e32 v41, v41
	s_nop 0
	v_pk_add_f32 v[168:169], v[34:35], v[36:37]
	v_pk_add_f32 v[170:171], v[38:39], v[40:41]
	v_cvt_pk_bf16_f32 v34, v34, v35
	v_cvt_pk_bf16_f32 v35, v36, v37
	v_cvt_pk_bf16_f32 v36, v38, v39
	v_cvt_pk_bf16_f32 v37, v40, v41
	v_exp_f32_e32 v42, v42
	v_exp_f32_e32 v43, v43
	v_exp_f32_e32 v44, v44
	s_waitcnt lgkmcnt(0)
	v_mfma_f32_32x32x16_bf16 v[2:17], v[34:37], v[208:211], v[2:17]
	v_exp_f32_e32 v45, v45
	v_exp_f32_e32 v46, v46
	v_exp_f32_e32 v47, v47
	v_mfma_f32_32x32x16_bf16 v[18:33], v[34:37], v[212:215], v[18:33]
	v_exp_f32_e32 v48, v48
	v_exp_f32_e32 v49, v49
	v_pk_add_f32 v[168:169], v[42:43], v[168:169]
	v_pk_add_f32 v[170:171], v[44:45], v[170:171]
	v_pk_add_f32 v[168:169], v[46:47], v[168:169]
	v_pk_add_f32 v[170:171], v[48:49], v[170:171]
	v_cvt_pk_bf16_f32 v38, v42, v43
	v_cvt_pk_bf16_f32 v39, v44, v45
	v_cvt_pk_bf16_f32 v40, v46, v47
	v_cvt_pk_bf16_f32 v41, v48, v49
	v_exp_f32_e32 v50, v50
	v_exp_f32_e32 v51, v51
	v_mfma_f32_32x32x16_bf16 v[2:17], v[38:41], v[224:227], v[2:17]
	v_exp_f32_e32 v52, v52
	v_exp_f32_e32 v53, v53
	v_exp_f32_e32 v54, v54
	v_mfma_f32_32x32x16_bf16 v[18:33], v[38:41], v[228:231], v[18:33]
	v_exp_f32_e32 v55, v55
	v_exp_f32_e32 v56, v56
	v_exp_f32_e32 v57, v57
	v_cvt_pk_bf16_f32 v240, v50, v51
	v_cvt_pk_bf16_f32 v241, v52, v53
	v_cvt_pk_bf16_f32 v242, v54, v55
	v_cvt_pk_bf16_f32 v243, v56, v57
	v_exp_f32_e32 v58, v58
	v_exp_f32_e32 v59, v59
	v_mfma_f32_32x32x16_bf16 v[2:17], v[240:243], v[216:219], v[2:17]
	v_exp_f32_e32 v60, v60
	v_exp_f32_e32 v61, v61
	v_exp_f32_e32 v62, v62
	v_mfma_f32_32x32x16_bf16 v[18:33], v[240:243], v[220:223], v[18:33]
	v_exp_f32_e32 v63, v63
	v_exp_f32_e32 v64, v64
	v_exp_f32_e32 v65, v65
	s_nop 0
	v_pk_add_f32 v[168:169], v[50:51], v[168:169]
	v_pk_add_f32 v[170:171], v[52:53], v[170:171]
	v_pk_add_f32 v[168:169], v[54:55], v[168:169]
	v_pk_add_f32 v[170:171], v[56:57], v[170:171]
	v_pk_add_f32 v[168:169], v[58:59], v[168:169]
	v_pk_add_f32 v[170:171], v[60:61], v[170:171]
	v_pk_add_f32 v[168:169], v[62:63], v[168:169]
	v_pk_add_f32 v[170:171], v[64:65], v[170:171]
	v_pk_add_f32 v[168:169], v[168:169], v[170:171]
	v_cvt_pk_bf16_f32 v54, v58, v59
	v_cvt_pk_bf16_f32 v55, v60, v61
	v_cvt_pk_bf16_f32 v56, v62, v63
	v_cvt_pk_bf16_f32 v57, v64, v65
	v_add_f32_e32 v168, v168, v169
	v_mov_b32_e32 v169, v168
	v_mfma_f32_32x32x16_bf16 v[2:17], v[54:57], v[232:235], v[2:17]
	s_nop 0
	v_permlane32_swap_b32_e32 v168, v169
	v_add_f32_e32 v168, v168, v169
	v_add_f32_e32 v126, v126, v168
	v_mfma_f32_32x32x16_bf16 v[18:33], v[54:57], v[236:239], v[18:33]
	s_add_u32 s12, s12, s8
	s_addc_u32 s13, s13, s9
	s_add_u32 s14, s14, s10
	s_addc_u32 s15, s15, s11
	s_cmp_eq_u32 s75, s21
	s_cbranch_scc1 .LBB1_327
	v_mov_b32_e32 v133, v0
	s_branch .LBB1_318
